# a15: + s_setprio 1 between attention barriers A' and B' (tail of QK + PV), 0 from B' to A'
# speedup vs baseline: 1.0240x; 1.0178x over previous
; #define KISSUE(k0) do { const char* kp_ = Kc + (size_t)(k0) * 384; _Pragma("unroll") for (int e = 0; e < 6; ++e) \
;       __builtin_amdgcn_global_load_lds((const unsigned*)(kp_ + ksrc[e]), (unsigned*)(K_lds + (wu * 6 + e) * 1024), 16, 0, 0); } while (0)
; #define ABAR() do { asm volatile("s_waitcnt vmcnt(0) lgkmcnt(0)" ::: "memory"); __builtin_amdgcn_s_barrier(); } while (0)
; DEVI void finishSM(f32x16& p0, f32x16& p1, float alpha, float& l_reg, bf16x8& pa0, bf16x8& pa1, bf16x8& pa2, bf16x8& pa3) {
;   float ps = 0;
; #pragma unroll
;   for (int r = 0; r < 16; ++r) ps += p0[r];
; #pragma unroll
;   for (int r = 0; r < 16; ++r) ps += p1[r];
;   { auto rr = __builtin_amdgcn_permlane32_swap(__float_as_uint(ps), __float_as_uint(ps), false, false);
;     ps = __uint_as_float(rr[0]) + __uint_as_float(rr[1]); }
;   l_reg = l_reg * alpha + ps;
;     ...
;   PK4(p0, 0, pa0); PK4(p0, 8, pa1); PK4(p1, 0, pa2); PK4(p1, 8, pa3);
; template <bool FIXED>
; DEVI void attn_task(const bf16_t* __restrict__ Qb, const bf16_t* __restrict__ Kh, const bf16_t* __restrict__ Vh, bf16_t* __restrict__ Ob, char* lds, float shiftC) {
;     ...
;   for (int j = 0; j < NT; ++j) {
;     f32x16 p0 = {}, p1 = {};
; #pragma unroll
;     for (int d0 = 0; d0 < 12; ++d0) {
;       const bf16x8 b0 = *(const bf16x8*)(Kr0 + (d0 >> 2) * 128 + kx[d0 & 3]);
;       const bf16x8 b1 = *(const bf16x8*)(Kr0 + 32 * 384 + (d0 >> 2) * 128 + kx[d0 & 3]);
;       p0 = __builtin_amdgcn_mfma_f32_32x32x16_bf16(b0, qr[d0], p0, 0, 0, 0);
;       p1 = __builtin_amdgcn_mfma_f32_32x32x16_bf16(b1, qr[d0], p1, 0, 0, 0);
;     }
;     ABAR();
;     if (j + 1 < NT) KISSUE((j + 1) * 64);
;     float mn, alpha = 1.f;
;     if constexpr (FIXED) {
; #pragma unroll
;       for (int r = 0; r < 16; ++r) p0[r] = __builtin_amdgcn_exp2f(p0[r]);
; #pragma unroll
;       for (int r = 0; r < 16; ++r) p1[r] = __builtin_amdgcn_exp2f(p1[r]);
.Lat7_top:
	s_waitcnt lgkmcnt(5)
	v_mfma_f32_32x32x16_bf16 v[210:225], v[186:189], v[142:145], 0
	ds_read_b128 v[186:189], v179 offset:128
	v_exp_f32_e32 v66, v66
	v_exp_f32_e32 v67, v67
	v_exp_f32_e32 v68, v68
	v_exp_f32_e32 v69, v69
	s_waitcnt lgkmcnt(5)
	v_mfma_f32_32x32x16_bf16 v[210:225], v[190:193], v[138:141], v[210:225]
	ds_read_b128 v[190:193], v178 offset:128
	v_exp_f32_e32 v70, v70
	v_add_f32_e32 v182, 0, v66
	v_exp_f32_e32 v71, v71
	v_add_f32_e32 v182, v67, v182
	s_waitcnt lgkmcnt(5)
	v_mfma_f32_32x32x16_bf16 v[210:225], v[194:197], v[134:137], v[210:225]
	ds_read_b128 v[194:197], v181 offset:256
	v_exp_f32_e32 v72, v72
	v_add_f32_e32 v182, v68, v182
	v_exp_f32_e32 v73, v73
	v_add_f32_e32 v182, v69, v182
	s_waitcnt lgkmcnt(5)
	v_mfma_f32_32x32x16_bf16 v[210:225], v[198:201], v[126:129], v[210:225]
	ds_read_b128 v[198:201], v180 offset:256
	v_exp_f32_e32 v74, v74
	v_add_f32_e32 v182, v70, v182
	v_exp_f32_e32 v75, v75
	v_add_f32_e32 v182, v71, v182
	s_waitcnt lgkmcnt(5)
	v_mfma_f32_32x32x16_bf16 v[210:225], v[202:205], v[130:133], v[210:225]
	ds_read_b128 v[202:205], v179 offset:256
	v_exp_f32_e32 v76, v76
	v_add_f32_e32 v182, v72, v182
	v_exp_f32_e32 v77, v77
	v_add_f32_e32 v182, v73, v182
	s_waitcnt lgkmcnt(5)
	v_mfma_f32_32x32x16_bf16 v[210:225], v[206:209], v[118:121], v[210:225]
	ds_read_b128 v[206:209], v178 offset:256
	v_exp_f32_e32 v78, v78
	v_add_f32_e32 v182, v74, v182
	v_exp_f32_e32 v79, v79
	v_add_f32_e32 v182, v75, v182
	s_waitcnt lgkmcnt(5)
	v_mfma_f32_32x32x16_bf16 v[210:225], v[186:189], v[122:125], v[210:225]
	ds_read_b128 v[186:189], v181 offset:12288
	v_exp_f32_e32 v80, v80
	v_add_f32_e32 v182, v76, v182
	v_exp_f32_e32 v81, v81
	v_add_f32_e32 v182, v77, v182
	s_waitcnt lgkmcnt(5)
	v_mfma_f32_32x32x16_bf16 v[210:225], v[190:193], v[110:113], v[210:225]
	ds_read_b128 v[190:193], v180 offset:12288
	v_add_f32_e32 v182, v78, v182
	v_add_f32_e32 v182, v79, v182
	v_add_f32_e32 v182, v80, v182
	v_add_f32_e32 v182, v81, v182
	s_waitcnt lgkmcnt(5)
	v_mfma_f32_32x32x16_bf16 v[210:225], v[194:197], v[114:117], v[210:225]
	ds_read_b128 v[194:197], v179 offset:12288
	v_cvt_pk_bf16_f32 v66, v66, v67
	v_cvt_pk_bf16_f32 v67, v68, v69
	v_cvt_pk_bf16_f32 v68, v70, v71
	v_cvt_pk_bf16_f32 v69, v72, v73
	s_waitcnt lgkmcnt(5)
	v_mfma_f32_32x32x16_bf16 v[210:225], v[198:201], v[106:109], v[210:225]
	ds_read_b128 v[198:201], v178 offset:12288
	v_cvt_pk_bf16_f32 v70, v74, v75
	v_cvt_pk_bf16_f32 v71, v76, v77
	v_cvt_pk_bf16_f32 v72, v78, v79
	v_cvt_pk_bf16_f32 v73, v80, v81
	s_waitcnt lgkmcnt(5)
	v_mfma_f32_32x32x16_bf16 v[210:225], v[202:205], v[102:105], v[210:225]
	ds_read_b128 v[202:205], v181 offset:12416
	v_permlane32_swap_b32_e32 v66, v68
	v_permlane32_swap_b32_e32 v67, v69
	v_exp_f32_e32 v82, v82
	v_exp_f32_e32 v83, v83
	s_waitcnt lgkmcnt(5)
	v_mfma_f32_32x32x16_bf16 v[210:225], v[206:209], v[98:101], v[210:225]
	ds_read_b128 v[206:209], v180 offset:12416
	v_exp_f32_e32 v84, v84
	v_permlane32_swap_b32_e32 v70, v72
	v_permlane32_swap_b32_e32 v71, v73
	v_exp_f32_e32 v85, v85
	s_waitcnt lgkmcnt(5)
	v_mfma_f32_32x32x16_bf16 v[226:241], v[186:189], v[142:145], 0
	ds_read_b128 v[186:189], v179 offset:12416
	v_exp_f32_e32 v86, v86
	v_add_f32_e32 v182, v82, v182
	v_exp_f32_e32 v87, v87
	v_add_f32_e32 v182, v83, v182
	s_waitcnt lgkmcnt(5)
	v_mfma_f32_32x32x16_bf16 v[226:241], v[190:193], v[138:141], v[226:241]
	ds_read_b128 v[190:193], v178 offset:12416
	v_exp_f32_e32 v88, v88
	v_add_f32_e32 v182, v84, v182
	v_exp_f32_e32 v89, v89
	v_add_f32_e32 v182, v85, v182
	s_waitcnt lgkmcnt(5)
	v_mfma_f32_32x32x16_bf16 v[226:241], v[194:197], v[134:137], v[226:241]
	ds_read_b128 v[194:197], v181 offset:12544
	v_exp_f32_e32 v90, v90
	v_add_f32_e32 v182, v86, v182
	v_exp_f32_e32 v91, v91
	v_add_f32_e32 v182, v87, v182
	s_waitcnt lgkmcnt(5)
	v_mfma_f32_32x32x16_bf16 v[226:241], v[198:201], v[126:129], v[226:241]
	ds_read_b128 v[198:201], v180 offset:12544
	v_exp_f32_e32 v92, v92
	v_add_f32_e32 v182, v88, v182
	v_exp_f32_e32 v93, v93
	v_add_f32_e32 v182, v89, v182
	s_waitcnt lgkmcnt(5)
	v_mfma_f32_32x32x16_bf16 v[226:241], v[202:205], v[130:133], v[226:241]
	ds_read_b128 v[202:205], v179 offset:12544
	v_exp_f32_e32 v94, v94
	v_add_f32_e32 v182, v90, v182
	v_exp_f32_e32 v95, v95
	v_add_f32_e32 v182, v91, v182
	s_waitcnt lgkmcnt(5)
	v_mfma_f32_32x32x16_bf16 v[226:241], v[206:209], v[118:121], v[226:241]
	ds_read_b128 v[206:209], v178 offset:12544
	v_exp_f32_e32 v96, v96
	v_add_f32_e32 v182, v92, v182
	v_exp_f32_e32 v97, v97
	v_add_f32_e32 v182, v93, v182
	s_waitcnt lgkmcnt(5)
	v_mfma_f32_32x32x16_bf16 v[226:241], v[186:189], v[122:125], v[226:241]
	s_waitcnt vmcnt(0) lgkmcnt(0)
	s_barrier
	s_setprio 1
	s_cmp_eq_u32 s62, 1
	s_cbranch_scc1 .Lat7_e_nok
	s_mov_b32 m0, s26
	s_nop 0
	global_load_lds_dwordx4 v152, s[98:99]
	global_load_lds_dwordx4 v154, s[98:99] offset:1024
	global_load_lds_dwordx4 v156, s[98:99] offset:2048
	global_load_lds_dwordx4 v158, s[98:99] offset:3072
	s_mov_b32 m0, s56
	s_nop 0
	global_load_lds_dwordx4 v160, s[98:99]
	global_load_lds_dwordx4 v162, s[98:99] offset:1024
	s_add_u32 s98, s98, 0x6000
	s_addc_u32 s99, s99, 0
; #define SBAR() __builtin_amdgcn_sched_barrier(0)
; DEVI void finishSM(f32x16& p0, f32x16& p1, float alpha, float& l_reg, bf16x8& pa0, bf16x8& pa1, bf16x8& pa2, bf16x8& pa3) {
;   float ps = 0;
; #pragma unroll
;   for (int r = 0; r < 16; ++r) ps += p0[r];
; #pragma unroll
;   for (int r = 0; r < 16; ++r) ps += p1[r];
;   { auto rr = __builtin_amdgcn_permlane32_swap(__float_as_uint(ps), __float_as_uint(ps), false, false);
;     ps = __uint_as_float(rr[0]) + __uint_as_float(rr[1]); }
;   l_reg = l_reg * alpha + ps;
;     ...
;   PK4(p0, 0, pa0); PK4(p0, 8, pa1); PK4(p1, 0, pa2); PK4(p1, 8, pa3);
;     ...
; }
; DEVI int v_st(int k) { const int kk = (k & ~0xC) | ((k & 4) << 1) | ((k & 8) >> 1); return ((kk >> 3) * 4) * 512 + ((kk & 7) * 32) * 2; }
; DEVI int v_rd_base(int lane) { return ((lane & 3) << 3) | (((lane >> 2) & 3) << 6) | (((lane >> 4) & 1) << 5) | (((lane >> 5) & 1) << 8); }
; template <int OFF> DEVI s16x4 tr_read(int vb) {
;   s16x4 r; asm volatile("ds_read_b64_tr_b16 %0, %1 offset:%2" : "=&v"(r) : "v"(vb), "i"(OFF) : "memory"); return r;
; }
; template <int D0> DEVI void pv_one(f32x16& od, int vb, bf16x8 pa0, bf16x8 pa1, bf16x8 pa2, bf16x8 pa3) {
;   const s16x4 l0 = tr_read<v_rd_off(D0, 0, 0)>(vb), h0 = tr_read<v_rd_off(D0, 0, 1)>(vb), l1 = tr_read<v_rd_off(D0, 1, 0)>(vb), h1 = tr_read<v_rd_off(D0, 1, 1)>(vb);
;   const s16x4 l2 = tr_read<v_rd_off(D0, 2, 0)>(vb), h2 = tr_read<v_rd_off(D0, 2, 1)>(vb), l3 = tr_read<v_rd_off(D0, 3, 0)>(vb), h3 = tr_read<v_rd_off(D0, 3, 1)>(vb);
;   asm volatile("s_waitcnt lgkmcnt(0)" ::: "memory"); SBAR();
;     ...
;   od = __builtin_amdgcn_mfma_f32_32x32x16_bf16(pa0, PK(l0, h0), od, 0, 0, 0);
;   od = __builtin_amdgcn_mfma_f32_32x32x16_bf16(pa1, PK(l1, h1), od, 0, 0, 0);
;   od = __builtin_amdgcn_mfma_f32_32x32x16_bf16(pa2, PK(l2, h2), od, 0, 0, 0);
;   od = __builtin_amdgcn_mfma_f32_32x32x16_bf16(pa3, PK(l3, h3), od, 0, 0, 0);
;     ...
; }
; template <bool FIXED>
; DEVI void attn_task(const bf16_t* __restrict__ Qb, const bf16_t* __restrict__ Kh, const bf16_t* __restrict__ Vh, bf16_t* __restrict__ Ob, char* lds, float shiftC) {
;     ...
;     pv_one<0>(o[0], vb0, pa0, pa1, pa2, pa3); pv_one<1>(o[1], vb0, pa0, pa1, pa2, pa3);
;     pv_one<2>(o[2], vb0, pa0, pa1, pa2, pa3); pv_one<3>(o[3], vb0, pa0, pa1, pa2, pa3);
;     ABAR();
;     if (j + 1 < NT) VISSUE((j + 1) * 64);
.Lat7_e_nok:
	v_add_f32_e32 v182, v94, v182
	v_add_f32_e32 v182, v95, v182
	v_add_f32_e32 v182, v96, v182
	ds_read_b64_tr_b16 v[186:187], v176 offset:4096
	ds_read_b64_tr_b16 v[188:189], v176 offset:6144
	v_mfma_f32_32x32x16_bf16 v[226:241], v[190:193], v[110:113], v[226:241]
	v_add_f32_e32 v182, v97, v182
	v_cvt_pk_bf16_f32 v74, v82, v83
	v_cvt_pk_bf16_f32 v75, v84, v85
	ds_read_b64_tr_b16 v[190:191], v176 offset:4608
	ds_read_b64_tr_b16 v[192:193], v176 offset:6656
	v_mfma_f32_32x32x16_bf16 v[226:241], v[194:197], v[114:117], v[226:241]
	v_cvt_pk_bf16_f32 v76, v86, v87
	v_cvt_pk_bf16_f32 v77, v88, v89
	v_cvt_pk_bf16_f32 v78, v90, v91
	ds_read_b64_tr_b16 v[194:195], v176 offset:0
	ds_read_b64_tr_b16 v[196:197], v176 offset:2048
	v_mfma_f32_32x32x16_bf16 v[226:241], v[198:201], v[106:109], v[226:241]
	v_cvt_pk_bf16_f32 v79, v92, v93
	v_cvt_pk_bf16_f32 v80, v94, v95
	v_cvt_pk_bf16_f32 v81, v96, v97
	ds_read_b64_tr_b16 v[198:199], v176 offset:512
	ds_read_b64_tr_b16 v[200:201], v176 offset:2560
	v_mfma_f32_32x32x16_bf16 v[226:241], v[202:205], v[102:105], v[226:241]
	v_add_f32_e32 v0, v0, v182
	v_permlane32_swap_b32_e32 v74, v76
	v_permlane32_swap_b32_e32 v75, v77
	ds_read_b64_tr_b16 v[202:203], v176 offset:1024
	ds_read_b64_tr_b16 v[204:205], v176 offset:3072
	v_mfma_f32_32x32x16_bf16 v[226:241], v[206:209], v[98:101], v[226:241]
	v_permlane32_swap_b32_e32 v78, v80
	v_permlane32_swap_b32_e32 v79, v81
	ds_read_b64_tr_b16 v[206:207], v176 offset:1536
	ds_read_b64_tr_b16 v[208:209], v176 offset:3584
	s_waitcnt lgkmcnt(6)
	v_mfma_f32_32x32x16_bf16 v[50:65], v[66:69], v[194:197], v[50:65]
	ds_read_b64_tr_b16 v[194:195], v176 offset:5120
	ds_read_b64_tr_b16 v[196:197], v176 offset:7168
	s_waitcnt lgkmcnt(6)
	v_mfma_f32_32x32x16_bf16 v[34:49], v[66:69], v[198:201], v[34:49]
	ds_read_b64_tr_b16 v[198:199], v176 offset:5632
	ds_read_b64_tr_b16 v[200:201], v176 offset:7680
	s_waitcnt lgkmcnt(6)
	v_mfma_f32_32x32x16_bf16 v[18:33], v[66:69], v[202:205], v[18:33]
	ds_read_b64_tr_b16 v[202:203], v176 offset:8192
	ds_read_b64_tr_b16 v[204:205], v176 offset:10240
	s_waitcnt lgkmcnt(6)
	v_mfma_f32_32x32x16_bf16 v[2:17], v[66:69], v[206:209], v[2:17]
	ds_read_b64_tr_b16 v[206:207], v176 offset:8704
	ds_read_b64_tr_b16 v[208:209], v176 offset:10752
	v_mfma_f32_32x32x16_bf16 v[50:65], v[70:73], v[186:189], v[50:65]
	ds_read_b64_tr_b16 v[186:187], v176 offset:9216
	ds_read_b64_tr_b16 v[188:189], v176 offset:11264
	v_mfma_f32_32x32x16_bf16 v[34:49], v[70:73], v[190:193], v[34:49]
	ds_read_b64_tr_b16 v[190:191], v176 offset:9728
	ds_read_b64_tr_b16 v[192:193], v176 offset:11776
	s_waitcnt lgkmcnt(10)
	v_mfma_f32_32x32x16_bf16 v[18:33], v[70:73], v[194:197], v[18:33]
	ds_read_b64_tr_b16 v[194:195], v176 offset:12288
	ds_read_b64_tr_b16 v[196:197], v176 offset:14336
	s_waitcnt lgkmcnt(10)
	v_mfma_f32_32x32x16_bf16 v[2:17], v[70:73], v[198:201], v[2:17]
	ds_read_b64_tr_b16 v[198:199], v176 offset:12800
	ds_read_b64_tr_b16 v[200:201], v176 offset:14848
	s_waitcnt lgkmcnt(10)
	v_mfma_f32_32x32x16_bf16 v[50:65], v[74:77], v[202:205], v[50:65]
	ds_read_b64_tr_b16 v[202:203], v176 offset:13312
	ds_read_b64_tr_b16 v[204:205], v176 offset:15360
	s_waitcnt lgkmcnt(10)
	v_mfma_f32_32x32x16_bf16 v[34:49], v[74:77], v[206:209], v[34:49]
	ds_read_b64_tr_b16 v[206:207], v176 offset:13824
	ds_read_b64_tr_b16 v[208:209], v176 offset:15872
	s_waitcnt lgkmcnt(10)
	v_mfma_f32_32x32x16_bf16 v[18:33], v[74:77], v[186:189], v[18:33]
	s_waitcnt lgkmcnt(8)
	v_mfma_f32_32x32x16_bf16 v[2:17], v[74:77], v[190:193], v[2:17]
	s_waitcnt lgkmcnt(6)
	v_mfma_f32_32x32x16_bf16 v[50:65], v[78:81], v[194:197], v[50:65]
	s_waitcnt vmcnt(0) lgkmcnt(0)
	s_barrier
	s_setprio 0
	s_mov_b32 m0, s58
	ds_read_b128 v[186:189], v181
	global_load_lds_dwordx4 v242, s[100:101]
	global_load_lds_dwordx4 v150, s[100:101] offset:1024
	global_load_lds_dwordx4 v243, s[100:101] offset:2048
	global_load_lds_dwordx4 v146, s[100:101] offset:3072
	s_add_u32 s100, s100, 0x4000
	s_addc_u32 s101, s101, 0
	ds_read_b128 v[190:193], v180
	ds_read_b128 v[194:197], v179
	v_mfma_f32_32x32x16_bf16 v[34:49], v[78:81], v[198:201], v[34:49]
	ds_read_b128 v[198:201], v178
	v_mfma_f32_32x32x16_bf16 v[18:33], v[78:81], v[202:205], v[18:33]
	ds_read_b128 v[202:205], v181 offset:128
	v_mfma_f32_32x32x16_bf16 v[2:17], v[78:81], v[206:209], v[2:17]
	ds_read_b128 v[206:209], v180 offset:128
	s_add_i32 s62, s62, -1
	s_cmp_eq_u32 s62, 0
	s_cbranch_scc1 .Lat7_done
; #define KISSUE(k0) do { const char* kp_ = Kc + (size_t)(k0) * 384; _Pragma("unroll") for (int e = 0; e < 6; ++e) \
;       __builtin_amdgcn_global_load_lds((const unsigned*)(kp_ + ksrc[e]), (unsigned*)(K_lds + (wu * 6 + e) * 1024), 16, 0, 0); } while (0)
; #define ABAR() do { asm volatile("s_waitcnt vmcnt(0) lgkmcnt(0)" ::: "memory"); __builtin_amdgcn_s_barrier(); } while (0)
; DEVI void finishSM(f32x16& p0, f32x16& p1, float alpha, float& l_reg, bf16x8& pa0, bf16x8& pa1, bf16x8& pa2, bf16x8& pa3) {
;   float ps = 0;
; #pragma unroll
;   for (int r = 0; r < 16; ++r) ps += p0[r];
; #pragma unroll
;   for (int r = 0; r < 16; ++r) ps += p1[r];
;   { auto rr = __builtin_amdgcn_permlane32_swap(__float_as_uint(ps), __float_as_uint(ps), false, false);
;     ps = __uint_as_float(rr[0]) + __uint_as_float(rr[1]); }
;   l_reg = l_reg * alpha + ps;
;     ...
;   PK4(p0, 0, pa0); PK4(p0, 8, pa1); PK4(p1, 0, pa2); PK4(p1, 8, pa3);
; template <bool FIXED>
; DEVI void attn_task(const bf16_t* __restrict__ Qb, const bf16_t* __restrict__ Kh, const bf16_t* __restrict__ Vh, bf16_t* __restrict__ Ob, char* lds, float shiftC) {
;     ...
;   for (int j = 0; j < NT; ++j) {
;     f32x16 p0 = {}, p1 = {};
; #pragma unroll
;     for (int d0 = 0; d0 < 12; ++d0) {
;       const bf16x8 b0 = *(const bf16x8*)(Kr0 + (d0 >> 2) * 128 + kx[d0 & 3]);
;       const bf16x8 b1 = *(const bf16x8*)(Kr0 + 32 * 384 + (d0 >> 2) * 128 + kx[d0 & 3]);
;       p0 = __builtin_amdgcn_mfma_f32_32x32x16_bf16(b0, qr[d0], p0, 0, 0, 0);
;       p1 = __builtin_amdgcn_mfma_f32_32x32x16_bf16(b1, qr[d0], p1, 0, 0, 0);
;     }
;     ABAR();
;     if (j + 1 < NT) KISSUE((j + 1) * 64);
;     float mn, alpha = 1.f;
;     if constexpr (FIXED) {
; #pragma unroll
;       for (int r = 0; r < 16; ++r) p0[r] = __builtin_amdgcn_exp2f(p0[r]);
; #pragma unroll
;       for (int r = 0; r < 16; ++r) p1[r] = __builtin_amdgcn_exp2f(p1[r]);
	s_waitcnt lgkmcnt(5)
	v_mfma_f32_32x32x16_bf16 v[66:81], v[186:189], v[142:145], 0
	ds_read_b128 v[186:189], v179 offset:128
	v_exp_f32_e32 v210, v210
	v_exp_f32_e32 v211, v211
	v_exp_f32_e32 v212, v212
	v_exp_f32_e32 v213, v213
	s_waitcnt lgkmcnt(5)
	v_mfma_f32_32x32x16_bf16 v[66:81], v[190:193], v[138:141], v[66:81]
	ds_read_b128 v[190:193], v178 offset:128
	v_exp_f32_e32 v214, v214
	v_add_f32_e32 v182, 0, v210
	v_exp_f32_e32 v215, v215
	v_add_f32_e32 v182, v211, v182
	s_waitcnt lgkmcnt(5)
	v_mfma_f32_32x32x16_bf16 v[66:81], v[194:197], v[134:137], v[66:81]
	ds_read_b128 v[194:197], v181 offset:256
	v_exp_f32_e32 v216, v216
	v_add_f32_e32 v182, v212, v182
	v_exp_f32_e32 v217, v217
	v_add_f32_e32 v182, v213, v182
	s_waitcnt lgkmcnt(5)
	v_mfma_f32_32x32x16_bf16 v[66:81], v[198:201], v[126:129], v[66:81]
	ds_read_b128 v[198:201], v180 offset:256
	v_exp_f32_e32 v218, v218
	v_add_f32_e32 v182, v214, v182
	v_exp_f32_e32 v219, v219
	v_add_f32_e32 v182, v215, v182
	s_waitcnt lgkmcnt(5)
	v_mfma_f32_32x32x16_bf16 v[66:81], v[202:205], v[130:133], v[66:81]
	ds_read_b128 v[202:205], v179 offset:256
	v_exp_f32_e32 v220, v220
	v_add_f32_e32 v182, v216, v182
	v_exp_f32_e32 v221, v221
	v_add_f32_e32 v182, v217, v182
	s_waitcnt lgkmcnt(5)
	v_mfma_f32_32x32x16_bf16 v[66:81], v[206:209], v[118:121], v[66:81]
	ds_read_b128 v[206:209], v178 offset:256
	v_exp_f32_e32 v222, v222
	v_add_f32_e32 v182, v218, v182
	v_exp_f32_e32 v223, v223
	v_add_f32_e32 v182, v219, v182
	s_waitcnt lgkmcnt(5)
	v_mfma_f32_32x32x16_bf16 v[66:81], v[186:189], v[122:125], v[66:81]
	ds_read_b128 v[186:189], v181 offset:12288
	v_exp_f32_e32 v224, v224
	v_add_f32_e32 v182, v220, v182
	v_exp_f32_e32 v225, v225
	v_add_f32_e32 v182, v221, v182
	s_waitcnt lgkmcnt(5)
	v_mfma_f32_32x32x16_bf16 v[66:81], v[190:193], v[110:113], v[66:81]
	ds_read_b128 v[190:193], v180 offset:12288
	v_add_f32_e32 v182, v222, v182
	v_add_f32_e32 v182, v223, v182
	v_add_f32_e32 v182, v224, v182
	v_add_f32_e32 v182, v225, v182
	s_waitcnt lgkmcnt(5)
	v_mfma_f32_32x32x16_bf16 v[66:81], v[194:197], v[114:117], v[66:81]
	ds_read_b128 v[194:197], v179 offset:12288
	v_cvt_pk_bf16_f32 v210, v210, v211
	v_cvt_pk_bf16_f32 v211, v212, v213
	v_cvt_pk_bf16_f32 v212, v214, v215
	v_cvt_pk_bf16_f32 v213, v216, v217
	s_waitcnt lgkmcnt(5)
	v_mfma_f32_32x32x16_bf16 v[66:81], v[198:201], v[106:109], v[66:81]
	ds_read_b128 v[198:201], v178 offset:12288
	v_cvt_pk_bf16_f32 v214, v218, v219
	v_cvt_pk_bf16_f32 v215, v220, v221
	v_cvt_pk_bf16_f32 v216, v222, v223
	v_cvt_pk_bf16_f32 v217, v224, v225
	s_waitcnt lgkmcnt(5)
	v_mfma_f32_32x32x16_bf16 v[66:81], v[202:205], v[102:105], v[66:81]
	ds_read_b128 v[202:205], v181 offset:12416
	v_permlane32_swap_b32_e32 v210, v212
	v_permlane32_swap_b32_e32 v211, v213
	v_exp_f32_e32 v226, v226
	v_exp_f32_e32 v227, v227
	s_waitcnt lgkmcnt(5)
	v_mfma_f32_32x32x16_bf16 v[66:81], v[206:209], v[98:101], v[66:81]
	ds_read_b128 v[206:209], v180 offset:12416
	v_exp_f32_e32 v228, v228
	v_permlane32_swap_b32_e32 v214, v216
	v_permlane32_swap_b32_e32 v215, v217
	v_exp_f32_e32 v229, v229
	s_waitcnt lgkmcnt(5)
	v_mfma_f32_32x32x16_bf16 v[82:97], v[186:189], v[142:145], 0
	ds_read_b128 v[186:189], v179 offset:12416
	v_exp_f32_e32 v230, v230
	v_add_f32_e32 v182, v226, v182
	v_exp_f32_e32 v231, v231
	v_add_f32_e32 v182, v227, v182
	s_waitcnt lgkmcnt(5)
	v_mfma_f32_32x32x16_bf16 v[82:97], v[190:193], v[138:141], v[82:97]
	ds_read_b128 v[190:193], v178 offset:12416
	v_exp_f32_e32 v232, v232
	v_add_f32_e32 v182, v228, v182
	v_exp_f32_e32 v233, v233
	v_add_f32_e32 v182, v229, v182
	s_waitcnt lgkmcnt(5)
	v_mfma_f32_32x32x16_bf16 v[82:97], v[194:197], v[134:137], v[82:97]
	ds_read_b128 v[194:197], v181 offset:12544
	v_exp_f32_e32 v234, v234
	v_add_f32_e32 v182, v230, v182
	v_exp_f32_e32 v235, v235
	v_add_f32_e32 v182, v231, v182
	s_waitcnt lgkmcnt(5)
	v_mfma_f32_32x32x16_bf16 v[82:97], v[198:201], v[126:129], v[82:97]
	ds_read_b128 v[198:201], v180 offset:12544
	v_exp_f32_e32 v236, v236
	v_add_f32_e32 v182, v232, v182
	v_exp_f32_e32 v237, v237
	v_add_f32_e32 v182, v233, v182
	s_waitcnt lgkmcnt(5)
	v_mfma_f32_32x32x16_bf16 v[82:97], v[202:205], v[130:133], v[82:97]
	ds_read_b128 v[202:205], v179 offset:12544
	v_exp_f32_e32 v238, v238
	v_add_f32_e32 v182, v234, v182
	v_exp_f32_e32 v239, v239
	v_add_f32_e32 v182, v235, v182
	s_waitcnt lgkmcnt(5)
	v_mfma_f32_32x32x16_bf16 v[82:97], v[206:209], v[118:121], v[82:97]
	ds_read_b128 v[206:209], v178 offset:12544
	v_exp_f32_e32 v240, v240
	v_add_f32_e32 v182, v236, v182
	v_exp_f32_e32 v241, v241
	v_add_f32_e32 v182, v237, v182
	s_waitcnt lgkmcnt(5)
	v_mfma_f32_32x32x16_bf16 v[82:97], v[186:189], v[122:125], v[82:97]
	s_waitcnt vmcnt(0) lgkmcnt(0)
	s_barrier
; #define SBAR() __builtin_amdgcn_sched_barrier(0)
; DEVI int crow(int r, int hi) { return (r & 3) + 8 * (r >> 2) + 4 * hi; }
; #define KISSUE(k0) do { const char* kp_ = Kc + (size_t)(k0) * 384; _Pragma("unroll") for (int e = 0; e < 6; ++e) \
;       __builtin_amdgcn_global_load_lds((const unsigned*)(kp_ + ksrc[e]), (unsigned*)(K_lds + (wu * 6 + e) * 1024), 16, 0, 0); } while (0)
; template <int D0> DEVI void pv_one(f32x16& od, int vb, bf16x8 pa0, bf16x8 pa1, bf16x8 pa2, bf16x8 pa3) {
;   const s16x4 l0 = tr_read<v_rd_off(D0, 0, 0)>(vb), h0 = tr_read<v_rd_off(D0, 0, 1)>(vb), l1 = tr_read<v_rd_off(D0, 1, 0)>(vb), h1 = tr_read<v_rd_off(D0, 1, 1)>(vb);
;   const s16x4 l2 = tr_read<v_rd_off(D0, 2, 0)>(vb), h2 = tr_read<v_rd_off(D0, 2, 1)>(vb), l3 = tr_read<v_rd_off(D0, 3, 0)>(vb), h3 = tr_read<v_rd_off(D0, 3, 1)>(vb);
;   asm volatile("s_waitcnt lgkmcnt(0)" ::: "memory"); SBAR();
;     ...
;   od = __builtin_amdgcn_mfma_f32_32x32x16_bf16(pa0, PK(l0, h0), od, 0, 0, 0);
;   od = __builtin_amdgcn_mfma_f32_32x32x16_bf16(pa1, PK(l1, h1), od, 0, 0, 0);
;   od = __builtin_amdgcn_mfma_f32_32x32x16_bf16(pa2, PK(l2, h2), od, 0, 0, 0);
;   od = __builtin_amdgcn_mfma_f32_32x32x16_bf16(pa3, PK(l3, h3), od, 0, 0, 0);
;     ...
; }
; template <bool FIXED>
; DEVI void attn_task(const bf16_t* __restrict__ Qb, const bf16_t* __restrict__ Kh, const bf16_t* __restrict__ Vh, bf16_t* __restrict__ Ob, char* lds, float shiftC) {
;     ...
;     ABAR();
;     if (j + 1 < NT) KISSUE((j + 1) * 64);
;     float mn, alpha = 1.f;
;     if constexpr (FIXED) {
; #pragma unroll
;       for (int r = 0; r < 16; ++r) p0[r] = __builtin_amdgcn_exp2f(p0[r]);
; #pragma unroll
;       for (int r = 0; r < 16; ++r) p1[r] = __builtin_amdgcn_exp2f(p1[r]);
;     } else partialSM(p0, p1, m_reg, mn, alpha);
;     if (!FIXED && __any(alpha < 1.f)) {
;       if (hi == 0) al_l[r32] = alpha;
;       asm volatile("s_waitcnt lgkmcnt(0)" ::: "memory");
; #pragma unroll
;       for (int r = 0; r < 16; ++r) { const float a = al_l[crow(r, hi)];
; #pragma unroll
;         for (int d = 0; d < 4; ++d) o[d][r] *= a; }
;     }
;     bf16x8 pa0, pa1, pa2, pa3;
;     finishSM(p0, p1, alpha, l_reg, pa0, pa1, pa2, pa3);
;     pv_one<0>(o[0], vb0, pa0, pa1, pa2, pa3); pv_one<1>(o[1], vb0, pa0, pa1, pa2, pa3);
;     pv_one<2>(o[2], vb0, pa0, pa1, pa2, pa3); pv_one<3>(o[3], vb0, pa0, pa1, pa2, pa3);
;     ABAR();
;     if (j + 1 < NT) VISSUE((j + 1) * 64);
	s_setprio 1
	s_mov_b32 m0, s26
	s_nop 0
	global_load_lds_dwordx4 v152, s[98:99]
	global_load_lds_dwordx4 v154, s[98:99] offset:1024
	global_load_lds_dwordx4 v156, s[98:99] offset:2048
	global_load_lds_dwordx4 v158, s[98:99] offset:3072
	s_mov_b32 m0, s56
	s_nop 0
	global_load_lds_dwordx4 v160, s[98:99]
	global_load_lds_dwordx4 v162, s[98:99] offset:1024
	s_add_u32 s98, s98, 0x6000
	s_addc_u32 s99, s99, 0
	v_add_f32_e32 v182, v238, v182
	v_add_f32_e32 v182, v239, v182
	v_add_f32_e32 v182, v240, v182
	ds_read_b64_tr_b16 v[186:187], v176 offset:4096
	ds_read_b64_tr_b16 v[188:189], v176 offset:6144
	v_mfma_f32_32x32x16_bf16 v[82:97], v[190:193], v[110:113], v[82:97]
	v_add_f32_e32 v182, v241, v182
	v_cvt_pk_bf16_f32 v218, v226, v227
	v_cvt_pk_bf16_f32 v219, v228, v229
	ds_read_b64_tr_b16 v[190:191], v176 offset:4608
	ds_read_b64_tr_b16 v[192:193], v176 offset:6656
	v_mfma_f32_32x32x16_bf16 v[82:97], v[194:197], v[114:117], v[82:97]
	v_cvt_pk_bf16_f32 v220, v230, v231
	v_cvt_pk_bf16_f32 v221, v232, v233
	v_cvt_pk_bf16_f32 v222, v234, v235
	ds_read_b64_tr_b16 v[194:195], v176 offset:0
	ds_read_b64_tr_b16 v[196:197], v176 offset:2048
	v_mfma_f32_32x32x16_bf16 v[82:97], v[198:201], v[106:109], v[82:97]
	v_cvt_pk_bf16_f32 v223, v236, v237
	v_cvt_pk_bf16_f32 v224, v238, v239
	v_cvt_pk_bf16_f32 v225, v240, v241
	ds_read_b64_tr_b16 v[198:199], v176 offset:512
	ds_read_b64_tr_b16 v[200:201], v176 offset:2560
	v_mfma_f32_32x32x16_bf16 v[82:97], v[202:205], v[102:105], v[82:97]
	v_add_f32_e32 v0, v0, v182
	v_permlane32_swap_b32_e32 v218, v220
	v_permlane32_swap_b32_e32 v219, v221
	ds_read_b64_tr_b16 v[202:203], v176 offset:1024
	ds_read_b64_tr_b16 v[204:205], v176 offset:3072
	v_mfma_f32_32x32x16_bf16 v[82:97], v[206:209], v[98:101], v[82:97]
	v_permlane32_swap_b32_e32 v222, v224
	v_permlane32_swap_b32_e32 v223, v225
	ds_read_b64_tr_b16 v[206:207], v176 offset:1536
	ds_read_b64_tr_b16 v[208:209], v176 offset:3584
	s_waitcnt lgkmcnt(6)
	v_mfma_f32_32x32x16_bf16 v[50:65], v[210:213], v[194:197], v[50:65]
	ds_read_b64_tr_b16 v[194:195], v176 offset:5120
	ds_read_b64_tr_b16 v[196:197], v176 offset:7168
	s_waitcnt lgkmcnt(6)
	v_mfma_f32_32x32x16_bf16 v[34:49], v[210:213], v[198:201], v[34:49]
	ds_read_b64_tr_b16 v[198:199], v176 offset:5632
	ds_read_b64_tr_b16 v[200:201], v176 offset:7680
	s_waitcnt lgkmcnt(6)
	v_mfma_f32_32x32x16_bf16 v[18:33], v[210:213], v[202:205], v[18:33]
	ds_read_b64_tr_b16 v[202:203], v176 offset:8192
	ds_read_b64_tr_b16 v[204:205], v176 offset:10240
	s_waitcnt lgkmcnt(6)
	v_mfma_f32_32x32x16_bf16 v[2:17], v[210:213], v[206:209], v[2:17]
	ds_read_b64_tr_b16 v[206:207], v176 offset:8704
	ds_read_b64_tr_b16 v[208:209], v176 offset:10752
	v_mfma_f32_32x32x16_bf16 v[50:65], v[214:217], v[186:189], v[50:65]
	ds_read_b64_tr_b16 v[186:187], v176 offset:9216
	ds_read_b64_tr_b16 v[188:189], v176 offset:11264
	v_mfma_f32_32x32x16_bf16 v[34:49], v[214:217], v[190:193], v[34:49]
	ds_read_b64_tr_b16 v[190:191], v176 offset:9728
	ds_read_b64_tr_b16 v[192:193], v176 offset:11776
	s_waitcnt lgkmcnt(10)
	v_mfma_f32_32x32x16_bf16 v[18:33], v[214:217], v[194:197], v[18:33]
	ds_read_b64_tr_b16 v[194:195], v176 offset:12288
	ds_read_b64_tr_b16 v[196:197], v176 offset:14336
	s_waitcnt lgkmcnt(10)
	v_mfma_f32_32x32x16_bf16 v[2:17], v[214:217], v[198:201], v[2:17]
	ds_read_b64_tr_b16 v[198:199], v176 offset:12800
	ds_read_b64_tr_b16 v[200:201], v176 offset:14848
	s_waitcnt lgkmcnt(10)
	v_mfma_f32_32x32x16_bf16 v[50:65], v[218:221], v[202:205], v[50:65]
	ds_read_b64_tr_b16 v[202:203], v176 offset:13312
	ds_read_b64_tr_b16 v[204:205], v176 offset:15360
	s_waitcnt lgkmcnt(10)
	v_mfma_f32_32x32x16_bf16 v[34:49], v[218:221], v[206:209], v[34:49]
	ds_read_b64_tr_b16 v[206:207], v176 offset:13824
	ds_read_b64_tr_b16 v[208:209], v176 offset:15872
	s_waitcnt lgkmcnt(10)
	v_mfma_f32_32x32x16_bf16 v[18:33], v[218:221], v[186:189], v[18:33]
	s_waitcnt lgkmcnt(8)
	v_mfma_f32_32x32x16_bf16 v[2:17], v[218:221], v[190:193], v[2:17]
	s_waitcnt lgkmcnt(6)
	v_mfma_f32_32x32x16_bf16 v[50:65], v[222:225], v[194:197], v[50:65]
	s_waitcnt vmcnt(0) lgkmcnt(0)
	s_barrier
	s_setprio 0
	s_mov_b32 m0, s58
	ds_read_b128 v[186:189], v181
	global_load_lds_dwordx4 v242, s[100:101]
	global_load_lds_dwordx4 v150, s[100:101] offset:1024
	global_load_lds_dwordx4 v243, s[100:101] offset:2048
	global_load_lds_dwordx4 v146, s[100:101] offset:3072
	s_add_u32 s100, s100, 0x4000
	s_addc_u32 s101, s101, 0
	ds_read_b128 v[190:193], v180
	ds_read_b128 v[194:197], v179
	v_mfma_f32_32x32x16_bf16 v[34:49], v[222:225], v[198:201], v[34:49]
	ds_read_b128 v[198:201], v178
	v_mfma_f32_32x32x16_bf16 v[18:33], v[222:225], v[202:205], v[18:33]
	ds_read_b128 v[202:205], v181 offset:128
	v_mfma_f32_32x32x16_bf16 v[2:17], v[222:225], v[206:209], v[2:17]
	ds_read_b128 v[206:209], v180 offset:128
	s_add_i32 s62, s62, -1
	s_branch .Lat7_top
